# setprio in GEMM loops + lazy running-max rescale (threshold 8) and permlane32_swap cross-half exchange in NSA selected far tiles
# speedup vs baseline: 1.0786x; 1.0241x over previous
; DI f32x16 mfma32(bf16x8 a, bf16x8 b, f32x16 c) { return __builtin_amdgcn_mfma_f32_32x32x16_bf16(a, b, c, 0, 0, 0); }
;     static DI int kmap(int kt) { return (kt >> 1) + 16 * (kt & 1); }
; template <class AL>
; DI void gemm_mainloop(f32x16 (&acc)[2][2], GemmRegs<AL>& G, bool pre, const AL& al, const u16* __restrict__ Bt, int ldb, int n0, int nk, char* sm,
;                       bool has_next, const AL& aln, int n0n) {
;     ...
;     auto compute = [&](const char* cA) {
;         const char* cB = cA + 16384;
;         bf16x8 a[2][2], b[2][2];
;         auto rd = [&](int set, int ks) {
; #pragma unroll
;             for (int mi = 0; mi < 2; ++mi) { const int row = wm * 64 + mi * 32 + r; a[set][mi] = *(const bf16x8*)(cA + row * 128 + (((2 * ks + h) ^ ((row >> 1) & 7)) << 4)); }
; #pragma unroll
;             for (int ni = 0; ni < 2; ++ni) { const int row = wn * 64 + ni * 32 + r; b[set][ni] = *(const bf16x8*)(cB + row * 128 + (((2 * ks + h) ^ ((row >> 1) & 7)) << 4)); }
;         };
;         auto mm = [&](int set) {
; #pragma unroll
;             for (int mi = 0; mi < 2; ++mi)
; #pragma unroll
;                 for (int ni = 0; ni < 2; ++ni) acc[mi][ni] = mfma32(a[set][mi], b[set][ni], acc[mi][ni]);
;         };
;         rd(0, 0); rd(1, 1);
;         __builtin_amdgcn_sched_barrier(0);
;         mm(0); rd(0, 2);
;         __builtin_amdgcn_sched_barrier(0);
;         mm(1); rd(1, 3);
;         __builtin_amdgcn_sched_barrier(0);
;         mm(0); mm(1);
;     };
;     ...
;     for (int kt = 0; kt < nk; kt += 2) {
;         compute(buf0);
;         store(RA1, RB1, kt + 1, buf1);
;         if (kt + 3 < nk) { al.load(RA1, AL::kmap(kt + 3)); loadB(RB1, AL::kmap(kt + 3)); }
;         else if (has_next) { aln.load(RA1, AL::kmap(1)); loadBn(RB1, AL::kmap(1)); }
;         __syncthreads();
;         compute(buf1);
;         if (kt + 2 < nk) {
;             store(RA0, RB0, kt + 2, buf0);
;             if (kt + 4 < nk) { al.load(RA0, AL::kmap(kt + 4)); loadB(RB0, AL::kmap(kt + 4)); }
;             else if (has_next) { aln.load(RA0, AL::kmap(0)); loadBn(RB0, AL::kmap(0)); }
;         }
;         __syncthreads();
;     }
.Lg1_loop:
	s_setprio 1
	v_add_u32_e32 v174, v168, v169
	v_add_u32_e32 v175, v170, v169
	v_add_u32_e32 v176, v168, v171
	v_add_u32_e32 v177, v170, v171
	ds_read_b128 v[150:153], v174
	ds_read_b128 v[154:157], v174 offset:4096
	ds_read_b128 v[158:161], v175 offset:16384
	ds_read_b128 v[162:165], v175 offset:20480
	ds_read_b128 v[180:183], v176
	ds_read_b128 v[184:187], v176 offset:4096
	ds_read_b128 v[188:191], v177 offset:16384
	ds_read_b128 v[192:195], v177 offset:20480
	s_mov_b32 m0, s58
	s_nop 0
	global_load_lds_dwordx4 v136, s[2:3]
	global_load_lds_dwordx4 v137, s[2:3] offset:1024
	global_load_lds_dwordx4 v138, s[2:3] offset:2048
	global_load_lds_dwordx4 v139, s[2:3] offset:3072
	s_add_u32 s2, s2, 0x80
	s_addc_u32 s3, s3, 0
	s_waitcnt lgkmcnt(5)
	v_mfma_f32_32x32x16_bf16 v[50:65], v[150:153], v[158:161], v[50:65]
	v_add_u32_e32 v178, v168, v172
	v_add_u32_e32 v179, v170, v172
	s_waitcnt lgkmcnt(4)
	v_mfma_f32_32x32x16_bf16 v[34:49], v[150:153], v[162:165], v[34:49]
	v_mfma_f32_32x32x16_bf16 v[18:33], v[154:157], v[158:161], v[18:33]
	v_mfma_f32_32x32x16_bf16 v[2:17], v[154:157], v[162:165], v[2:17]
	ds_read_b128 v[150:153], v178
	ds_read_b128 v[154:157], v178 offset:4096
	ds_read_b128 v[158:161], v179 offset:16384
	ds_read_b128 v[162:165], v179 offset:20480
	s_mov_b32 m0, s59
	s_nop 0
	global_load_lds_dwordx4 v136, s[64:65]
	global_load_lds_dwordx4 v137, s[64:65] offset:1024
	global_load_lds_dwordx4 v138, s[64:65] offset:2048
	global_load_lds_dwordx4 v139, s[64:65] offset:3072
	s_add_u32 s64, s64, 0x80
	s_addc_u32 s65, s65, 0
	s_waitcnt lgkmcnt(5)
	v_mfma_f32_32x32x16_bf16 v[50:65], v[180:183], v[188:191], v[50:65]
	s_waitcnt lgkmcnt(4)
	v_mfma_f32_32x32x16_bf16 v[34:49], v[180:183], v[192:195], v[34:49]
	v_add_u32_e32 v180, v168, v173
	v_add_u32_e32 v181, v170, v173
	v_mfma_f32_32x32x16_bf16 v[18:33], v[184:187], v[188:191], v[18:33]
	v_mfma_f32_32x32x16_bf16 v[2:17], v[184:187], v[192:195], v[2:17]
	ds_read_b128 v[182:185], v180
	ds_read_b128 v[186:189], v180 offset:4096
	ds_read_b128 v[190:193], v181 offset:16384
	ds_read_b128 v[194:197], v181 offset:20480
	s_waitcnt lgkmcnt(5)
	v_mfma_f32_32x32x16_bf16 v[50:65], v[150:153], v[158:161], v[50:65]
	s_waitcnt lgkmcnt(4)
	v_mfma_f32_32x32x16_bf16 v[34:49], v[150:153], v[162:165], v[34:49]
	v_mfma_f32_32x32x16_bf16 v[18:33], v[154:157], v[158:161], v[18:33]
	v_mfma_f32_32x32x16_bf16 v[2:17], v[154:157], v[162:165], v[2:17]
	s_waitcnt lgkmcnt(1)
	v_mfma_f32_32x32x16_bf16 v[50:65], v[182:185], v[190:193], v[50:65]
	s_waitcnt lgkmcnt(0)
	v_mfma_f32_32x32x16_bf16 v[34:49], v[182:185], v[194:197], v[34:49]
	v_mfma_f32_32x32x16_bf16 v[18:33], v[186:189], v[190:193], v[18:33]
	v_mfma_f32_32x32x16_bf16 v[2:17], v[186:189], v[194:197], v[2:17]
	s_waitcnt vmcnt(0)
	s_barrier
	s_mov_b32 s53, 1
	s_cmp_lt_u32 s43, 14
	s_cbranch_scc1 .Lg1_bgo
	s_mov_b32 s53, 0
	s_and_b64 vcc, exec, s[0:1]
	s_cbranch_vccz .Lg1_bgo
	s_mov_b32 s53, 1
	s_lshl_b32 s26, s94, 18
	s_add_u32 s2, s6, s26
	s_addc_u32 s3, s7, 0
	s_lshl_b32 s26, s93, 18
	s_add_u32 s64, s8, s26
	s_addc_u32 s65, s9, 0

;     static DI int kmap(int kt) { return (kt >> 1) + 16 * (kt & 1); }
; template <class AL>
; DI void gemm_mainloop(f32x16 (&acc)[2][2], GemmRegs<AL>& G, bool pre, const AL& al, const u16* __restrict__ Bt, int ldb, int n0, int nk, char* sm,
;                       bool has_next, const AL& aln, int n0n) {
;     ...
;     for (int kt = 0; kt < nk; kt += 2) {
;         compute(buf0);
;         store(RA1, RB1, kt + 1, buf1);
;         if (kt + 3 < nk) { al.load(RA1, AL::kmap(kt + 3)); loadB(RB1, AL::kmap(kt + 3)); }
;         else if (has_next) { aln.load(RA1, AL::kmap(1)); loadBn(RB1, AL::kmap(1)); }
;         __syncthreads();
;         compute(buf1);
;         if (kt + 2 < nk) {
;             store(RA0, RB0, kt + 2, buf0);
;             if (kt + 4 < nk) { al.load(RA0, AL::kmap(kt + 4)); loadB(RB0, AL::kmap(kt + 4)); }
;             else if (has_next) { aln.load(RA0, AL::kmap(0)); loadBn(RB0, AL::kmap(0)); }
;         }
;         __syncthreads();
;     }
.Lg1_skipB:
	s_waitcnt lgkmcnt(5)
	v_mfma_f32_32x32x16_bf16 v[50:65], v[182:185], v[190:193], v[50:65]
	s_waitcnt lgkmcnt(4)
	v_mfma_f32_32x32x16_bf16 v[34:49], v[182:185], v[174:177], v[34:49]
	v_mfma_f32_32x32x16_bf16 v[18:33], v[186:189], v[190:193], v[18:33]
	v_mfma_f32_32x32x16_bf16 v[2:17], v[186:189], v[174:177], v[2:17]
	ds_read_b128 v[174:177], v180 offset:32768
	ds_read_b128 v[182:185], v180 offset:36864
	ds_read_b128 v[186:189], v181 offset:49152
	ds_read_b128 v[178:181], v181 offset:53248
	s_waitcnt lgkmcnt(5)
	v_mfma_f32_32x32x16_bf16 v[50:65], v[150:153], v[158:161], v[50:65]
	s_waitcnt lgkmcnt(4)
	v_mfma_f32_32x32x16_bf16 v[34:49], v[150:153], v[162:165], v[34:49]
	v_mfma_f32_32x32x16_bf16 v[18:33], v[154:157], v[158:161], v[18:33]
	v_mfma_f32_32x32x16_bf16 v[2:17], v[154:157], v[162:165], v[2:17]
	s_waitcnt lgkmcnt(1)
	v_mfma_f32_32x32x16_bf16 v[50:65], v[174:177], v[186:189], v[50:65]
	s_waitcnt lgkmcnt(0)
	v_mfma_f32_32x32x16_bf16 v[34:49], v[174:177], v[178:181], v[34:49]
	v_mfma_f32_32x32x16_bf16 v[18:33], v[182:185], v[186:189], v[18:33]
	v_mfma_f32_32x32x16_bf16 v[2:17], v[182:185], v[178:181], v[2:17]
	s_waitcnt vmcnt(0)
	s_barrier
	s_add_i32 s43, s43, 2
	s_cmp_lt_u32 s43, 16
	s_cbranch_scc1 .Lg1_loop
	s_setprio 0

; DI float fexp2(float x) { return __builtin_amdgcn_exp2f(x); }
; DI f32x16 mfma32(bf16x8 a, bf16x8 b, f32x16 c) { return __builtin_amdgcn_mfma_f32_32x32x16_bf16(a, b, c, 0, 0, 0); }
; DI f32x16 zero16() { f32x16 z; for (int i = 0; i < 16; ++i) z[i] = 0.f; return z; }
; template <int MASK, bool NEAR, int PASS>
; DI void flash_tile(Flash& st, const bf16x8 (&qf)[4], const char* kbuf, const char* vbuf, int pos0, int qpos, bool on,
;                    const float* lut, float bfar, float* imp_row, float rinv) {
;     ...
;     for (int ks = 0; ks < 4; ++ks) {
;         const int ka = r * 128 + (((2 * ks + h) ^ ((r >> 1) & 7)) << 4);
;         const bf16x8 a0 = *(const bf16x8*)(kbuf + ka);
;         const bf16x8 a1 = *(const bf16x8*)(kbuf + 4096 + ka);
;         s[0] = mfma32(a0, qf[ks], s[0]);
;         s[1] = mfma32(a1, qf[ks], s[1]);
;     }
;     constexpr float c1 = 0.125f * LOG2E;
;     float alpha = 1.f;
;     float rs = 0.f;
;     if (!NEAR) {
;         const float bc = MASK == 2 ? 0.f : bfar;
;         float mref;
;         if (PASS != 2) {
;             float mr = s[0][0];
; #pragma unroll
;             for (int i = 1; i < 16; ++i) mr = fmaxf(mr, s[0][i]);
; #pragma unroll
;             for (int i = 0; i < 16; ++i) mr = fmaxf(mr, s[1][i]);
;             float mx = on ? mr * c1 + bc : -1e30f;
;             mx = fmaxf(mx, __shfl_xor(mx, 32));
;             const float mnew = fmaxf(st.m, mx);
;             alpha = fexp2(st.m - mnew);
;             st.m = mnew;
;             mref = mnew;
;         } else mref = st.m;
;         float bm = on ? bc - mref : -1e30f;
;         if (PASS == 2) bm = on ? bm + __log2f(rinv) : -1e30f;
; #pragma unroll
;         for (int tt = 0; tt < 2; ++tt)
; #pragma unroll
;             for (int i = 0; i < 16; ++i) { const float pv = fexp2(s[tt][i] * c1 + bm); s[tt][i] = pv; rs += pv; }
;     ...
;     if (PASS != 2) {
;         rs += __shfl_xor(rs, 32);
;         st.l = st.l * alpha + rs;
;     }
;     f32x16 ia = zero16();
;     if (PASS != 1) {
;         if (PASS == 0) {
; #pragma unroll
;             for (int i = 0; i < 16; ++i) { st.o0[i] *= alpha; st.o1[i] *= alpha; }
;         }
.LBB0_1366:
	s_ashr_i32 s2, s22, 6
	s_cmpk_gt_i32 s2, 0x7f
	s_cselect_b64 vcc, -1, 0
	s_cmp_lt_i32 s2, 64
	s_cselect_b64 s[0:1], -1, 0
	v_cndmask_b32_e64 v5, v1, v157, s[0:1]
	v_cndmask_b32_e64 v4, v154, v174, s[0:1]
	v_lshrrev_b64 v[4:5], s2, v[4:5]
	v_and_b32_e32 v2, 1, v4
	v_cmp_eq_u32_e64 s[0:1], 1, v2
	s_and_b64 s[0:1], s[8:9], s[0:1]
	v_cndmask_b32_e64 v180, 0, 1, s[8:9]
	v_cndmask_b32_e64 v2, 0, 1, s[0:1]
	v_cndmask_b32_e32 v2, v2, v180, vcc
	v_and_b32_e32 v2, 1, v2
	v_cmp_eq_u32_e64 s[0:1], 1, v2
	v_cmp_ne_u32_e32 vcc, 0, v2
	s_cbranch_vccz .LBB0_1372
	ds_read_b128 v[50:53], v190
	ds_read_b128 v[138:141], v190 offset:4096
	ds_read_b128 v[150:153], v191
	ds_read_b128 v[12:15], v191 offset:4096
	ds_read_b128 v[146:149], v192
	ds_read_b128 v[8:11], v192 offset:4096
	ds_read_b128 v[142:145], v193
	ds_read_b128 v[4:7], v193 offset:4096
	s_add_i32 s2, s22, 0xb0
	v_cmp_le_i32_e32 vcc, s2, v226
	s_and_saveexec_b64 s[2:3], vcc
	s_xor_b64 s[2:3], exec, s[2:3]
	s_cbranch_execz .LBB0_1369
	s_waitcnt lgkmcnt(7)
	v_mfma_f32_32x32x16_bf16 v[66:81], v[50:53], v[94:97], 0
	s_waitcnt lgkmcnt(5)
	v_mfma_f32_32x32x16_bf16 v[66:81], v[150:153], v[98:101], v[66:81]
	v_mfma_f32_32x32x16_bf16 v[50:65], v[138:141], v[94:97], 0
	s_waitcnt lgkmcnt(3)
	v_mfma_f32_32x32x16_bf16 v[66:81], v[146:149], v[102:105], v[66:81]
	v_mfma_f32_32x32x16_bf16 v[50:65], v[12:15], v[98:101], v[50:65]
	s_waitcnt lgkmcnt(1)
	v_mfma_f32_32x32x16_bf16 v[66:81], v[142:145], v[106:109], v[66:81]
	v_mfma_f32_32x32x16_bf16 v[50:65], v[8:11], v[102:105], v[50:65]
	s_nop 10
	v_max3_f32 v2, v66, v67, v68
	v_max_f32_e32 v2, v2, v69
	v_max3_f32 v2, v2, v70, v71
	v_max3_f32 v2, v2, v72, v73
	v_max3_f32 v2, v2, v74, v75
	s_waitcnt lgkmcnt(0)
	v_mfma_f32_32x32x16_bf16 v[50:65], v[4:7], v[106:109], v[50:65]
	v_max3_f32 v2, v2, v76, v77
	v_max3_f32 v2, v2, v78, v79
	v_max3_f32 v2, v2, v80, v81
	s_nop 8
	v_max3_f32 v2, v2, v50, v51
	v_max3_f32 v2, v2, v52, v53
	v_max3_f32 v2, v2, v54, v55
	v_max3_f32 v2, v2, v56, v57
	v_max3_f32 v2, v2, v58, v59
	v_max3_f32 v2, v2, v60, v61
	v_max3_f32 v2, v2, v62, v63
	v_max3_f32 v2, v2, v64, v65
	v_fmamk_f32 v2, v2, 0x3e38aa3b, v225
	v_cndmask_b32_e64 v2, v215, v2, s[0:1]
	v_mov_b32_e32 v4, v2
	s_nop 1
	v_permlane32_swap_b32_e32 v2, v4
	v_max3_f32 v138, v181, v2, v4
	v_sub_f32_e32 v4, v138, v181
	v_cmp_lt_f32_e32 vcc, 0x41000000, v4
	v_cndmask_b32_e32 v138, v181, v138, vcc
	s_mov_b64 s[100:101], vcc
	v_sub_f32_e32 v4, v225, v138
	v_cndmask_b32_e64 v139, v215, v4, s[0:1]
	v_fmamk_f32 v4, v66, 0x3e38aa3b, v139
	v_exp_f32_e32 v8, v4
	v_fmamk_f32 v4, v67, 0x3e38aa3b, v139
	v_exp_f32_e32 v12, v4
	v_fmamk_f32 v4, v68, 0x3e38aa3b, v139
	v_exp_f32_e32 v9, v4
	v_fmamk_f32 v4, v69, 0x3e38aa3b, v139
	v_exp_f32_e32 v13, v4
	v_fmamk_f32 v4, v70, 0x3e38aa3b, v139
	v_exp_f32_e32 v10, v4
	v_fmamk_f32 v4, v71, 0x3e38aa3b, v139
	v_exp_f32_e32 v14, v4
	v_fmamk_f32 v4, v72, 0x3e38aa3b, v139
	v_exp_f32_e32 v11, v4
	v_fmamk_f32 v4, v73, 0x3e38aa3b, v139
	v_exp_f32_e32 v15, v4
	v_fmamk_f32 v4, v74, 0x3e38aa3b, v139
	v_exp_f32_e32 v66, v4
	v_fmamk_f32 v4, v75, 0x3e38aa3b, v139
	v_exp_f32_e32 v67, v4
	v_fmamk_f32 v4, v76, 0x3e38aa3b, v139
	v_exp_f32_e32 v68, v4
	v_fmamk_f32 v4, v77, 0x3e38aa3b, v139
	v_exp_f32_e32 v69, v4
	v_fmamk_f32 v4, v78, 0x3e38aa3b, v139
	v_exp_f32_e32 v70, v4
	v_fmamk_f32 v4, v79, 0x3e38aa3b, v139
	v_exp_f32_e32 v71, v4
	v_fmamk_f32 v4, v80, 0x3e38aa3b, v139
	v_exp_f32_e32 v72, v4
	v_add_f32_e32 v4, v12, v8
	v_add_f32_e32 v4, v9, v4
	v_add_f32_e32 v4, v13, v4
	v_add_f32_e32 v4, v10, v4
	v_add_f32_e32 v4, v14, v4
	v_add_f32_e32 v4, v11, v4
	v_add_f32_e32 v4, v15, v4
	v_add_f32_e32 v4, v66, v4
	v_add_f32_e32 v4, v67, v4
	v_fmamk_f32 v5, v81, 0x3e38aa3b, v139
	v_add_f32_e32 v4, v68, v4
	v_add_f32_e32 v4, v69, v4
	v_exp_f32_e32 v73, v5
	v_fmamk_f32 v5, v50, 0x3e38aa3b, v139
	v_add_f32_e32 v4, v70, v4
	v_exp_f32_e32 v50, v5
	v_fmamk_f32 v5, v51, 0x3e38aa3b, v139
	v_add_f32_e32 v4, v71, v4
	v_exp_f32_e32 v51, v5
	v_fmamk_f32 v5, v52, 0x3e38aa3b, v139
	v_add_f32_e32 v4, v72, v4
	v_exp_f32_e32 v52, v5
	v_fmamk_f32 v5, v53, 0x3e38aa3b, v139
	v_add_f32_e32 v4, v73, v4
	v_exp_f32_e32 v53, v5
	v_fmamk_f32 v5, v54, 0x3e38aa3b, v139
	v_add_f32_e32 v4, v50, v4
	v_exp_f32_e32 v54, v5
	v_fmamk_f32 v5, v55, 0x3e38aa3b, v139
	v_add_f32_e32 v4, v51, v4
	v_exp_f32_e32 v55, v5
	v_fmamk_f32 v5, v56, 0x3e38aa3b, v139
	v_add_f32_e32 v4, v52, v4
	v_exp_f32_e32 v56, v5
	v_fmamk_f32 v5, v57, 0x3e38aa3b, v139
	v_add_f32_e32 v4, v53, v4
	v_exp_f32_e32 v57, v5
	v_fmamk_f32 v5, v58, 0x3e38aa3b, v139
	v_add_f32_e32 v4, v54, v4
	v_exp_f32_e32 v58, v5
	v_fmamk_f32 v5, v59, 0x3e38aa3b, v139
	v_add_f32_e32 v4, v55, v4
	v_exp_f32_e32 v59, v5
	v_fmamk_f32 v5, v60, 0x3e38aa3b, v139
	v_add_f32_e32 v4, v56, v4
	v_exp_f32_e32 v60, v5
	v_add_f32_e32 v4, v57, v4
	v_add_f32_e32 v4, v58, v4
	v_add_f32_e32 v4, v59, v4
	v_sub_f32_e32 v2, v181, v138
	v_add_f32_e32 v74, v60, v4
	v_fmamk_f32 v4, v61, 0x3e38aa3b, v139
	v_exp_f32_e32 v2, v2
	v_exp_f32_e32 v61, v4
	ds_read_b64_tr_b16 v[4:5], v194 offset:8192
	ds_read_b64_tr_b16 v[6:7], v194 offset:9216
	v_cvt_pk_bf16_f32 v11, v11, v15
	v_cvt_pk_bf16_f32 v10, v10, v14
	v_cvt_pk_bf16_f32 v9, v9, v13
	v_cvt_pk_bf16_f32 v8, v8, v12
	ds_read_b64_tr_b16 v[14:15], v194 offset:9280
	ds_read_b64_tr_b16 v[12:13], v194 offset:8256
	s_cmp_eq_u64 s[100:101], 0
	s_cbranch_scc1 .Llz_selA
	v_pk_mul_f32 v[48:49], v[48:49], v[2:3] op_sel_hi:[1,0]
	v_pk_mul_f32 v[46:47], v[46:47], v[2:3] op_sel_hi:[1,0]
	v_pk_mul_f32 v[44:45], v[44:45], v[2:3] op_sel_hi:[1,0]
	v_pk_mul_f32 v[42:43], v[42:43], v[2:3] op_sel_hi:[1,0]
	v_pk_mul_f32 v[40:41], v[40:41], v[2:3] op_sel_hi:[1,0]
	v_pk_mul_f32 v[38:39], v[38:39], v[2:3] op_sel_hi:[1,0]
	v_pk_mul_f32 v[36:37], v[36:37], v[2:3] op_sel_hi:[1,0]
	v_pk_mul_f32 v[34:35], v[34:35], v[2:3] op_sel_hi:[1,0]
	v_pk_mul_f32 v[32:33], v[32:33], v[2:3] op_sel_hi:[1,0]
	v_pk_mul_f32 v[30:31], v[30:31], v[2:3] op_sel_hi:[1,0]
	v_pk_mul_f32 v[28:29], v[28:29], v[2:3] op_sel_hi:[1,0]
	v_pk_mul_f32 v[26:27], v[26:27], v[2:3] op_sel_hi:[1,0]
	v_pk_mul_f32 v[24:25], v[24:25], v[2:3] op_sel_hi:[1,0]
	v_pk_mul_f32 v[22:23], v[22:23], v[2:3] op_sel_hi:[1,0]
	v_pk_mul_f32 v[20:21], v[20:21], v[2:3] op_sel_hi:[1,0]
	v_pk_mul_f32 v[18:19], v[18:19], v[2:3] op_sel_hi:[1,0]
; DI f32x16 mfma32(bf16x8 a, bf16x8 b, f32x16 c) { return __builtin_amdgcn_mfma_f32_32x32x16_bf16(a, b, c, 0, 0, 0); }
; DI int opaque(int v) { asm volatile("" : "+v"(v)); return v; }
; template <int MASK, bool NEAR, int PASS>
; DI void flash_tile(Flash& st, const bf16x8 (&qf)[4], const char* kbuf, const char* vbuf, int pos0, int qpos, bool on,
;                    const float* lut, float bfar, float* imp_row, float rinv) {
;     ...
;     if (PASS != 2) {
;         rs += __shfl_xor(rs, 32);
;         st.l = st.l * alpha + rs;
;     }
;     ...
;         const int G = lane >> 4, i16 = lane & 15, q = i16 >> 2, pp = i16 & 3;
;         const char* vb = vbuf + (4 * (G >> 1) + q) * 128 + (16 * (G & 1) + 4 * pp) * 2;
; #pragma unroll
;         for (int tt = 0; tt < 2; ++tt)
; #pragma unroll
;             for (int ss = 0; ss < 2; ++ss) {
;                 f32x4 pa = {s[tt][8 * ss], s[tt][8 * ss + 1], s[tt][8 * ss + 2], s[tt][8 * ss + 3]};
;                 f32x4 pb2 = {s[tt][8 * ss + 4], s[tt][8 * ss + 5], s[tt][8 * ss + 6], s[tt][8 * ss + 7]};
;                 const bf16x8 pfrag = cvt8(pa, pb2);
;                 const char* vk = vb + (32 * tt + 16 * ss) * 128;
;                 if (PASS == 2) {
;                     const int d = opaque((lane & 31) - h) - (8 * tt + 4 * ss);
;                     const unsigned one2 = 0x3F803F80u, oneh = 0x3F800000u;
;                     const uint4 ov = {d == 0 ? one2 : 0u, d == 0 ? one2 : (d == 1 ? oneh : 0u), d == 2 ? one2 : 0u, d == 2 ? one2 : (d == 3 ? oneh : 0u)};
;                     ia = mfma32(__builtin_bit_cast(bf16x8, ov), pfrag, ia);
;                 }
;                 {
;                     const s16x4 lo = tr_read(vk), hi = tr_read(vk + 8 * 128);
;                     const bf16x8 va = __builtin_shufflevector(lo, hi, 0, 1, 2, 3, 4, 5, 6, 7);
;                     st.o0 = mfma32(va, pfrag, st.o0);
;                 }
;                 {
;                     const s16x4 lo = tr_read(vk + 64), hi = tr_read(vk + 8 * 128 + 64);
;                     const bf16x8 va = __builtin_shufflevector(lo, hi, 0, 1, 2, 3, 4, 5, 6, 7);
;                     st.o1 = mfma32(va, pfrag, st.o1);
;                 }
;             }
.Llz_selA:
	s_waitcnt lgkmcnt(2)
	v_mfma_f32_32x32x16_bf16 v[34:49], v[4:7], v[8:11], v[34:49]
	ds_read_b64_tr_b16 v[4:5], v194 offset:10240
	ds_read_b64_tr_b16 v[6:7], v194 offset:11264
	v_fmamk_f32 v64, v64, 0x3e38aa3b, v139
	v_exp_f32_e32 v64, v64
	v_add_f32_e32 v74, v61, v74
	v_mov_b32_e32 v181, v138
	s_waitcnt lgkmcnt(2)
	v_mfma_f32_32x32x16_bf16 v[18:33], v[12:15], v[8:11], v[18:33]
	ds_read_b64_tr_b16 v[14:15], v194 offset:11328
	ds_read_b64_tr_b16 v[12:13], v194 offset:10304
	v_cvt_pk_bf16_f32 v11, v72, v73
	v_cvt_pk_bf16_f32 v10, v70, v71
	v_cvt_pk_bf16_f32 v9, v68, v69
	v_cvt_pk_bf16_f32 v8, v66, v67
	s_waitcnt lgkmcnt(2)
	s_nop 0
	v_mfma_f32_32x32x16_bf16 v[34:49], v[4:7], v[8:11], v[34:49]
	v_fmamk_f32 v4, v62, 0x3e38aa3b, v139
	v_exp_f32_e32 v62, v4
	v_fmamk_f32 v4, v63, 0x3e38aa3b, v139
	v_exp_f32_e32 v63, v4
	ds_read_b64_tr_b16 v[4:5], v194 offset:12288
	ds_read_b64_tr_b16 v[6:7], v194 offset:13312
	v_fmac_f32_e32 v139, 0x3e38aa3b, v65
	s_waitcnt lgkmcnt(2)
	v_mfma_f32_32x32x16_bf16 v[18:33], v[12:15], v[8:11], v[18:33]
	ds_read_b64_tr_b16 v[14:15], v194 offset:13376
	ds_read_b64_tr_b16 v[12:13], v194 offset:12352
	v_cvt_pk_bf16_f32 v11, v56, v57
	v_cvt_pk_bf16_f32 v10, v54, v55
	v_cvt_pk_bf16_f32 v9, v52, v53
	v_cvt_pk_bf16_f32 v8, v50, v51
	v_exp_f32_e32 v51, v139
	s_waitcnt lgkmcnt(2)
	v_mfma_f32_32x32x16_bf16 v[34:49], v[4:7], v[8:11], v[34:49]
	v_add_f32_e32 v4, v62, v74
	v_add_f32_e32 v4, v63, v4
	v_add_f32_e32 v50, v64, v4
	ds_read_b64_tr_b16 v[4:5], v194 offset:14336
	ds_read_b64_tr_b16 v[6:7], v194 offset:15360
	v_add_f32_e32 v50, v51, v50
	s_waitcnt lgkmcnt(2)
	v_mfma_f32_32x32x16_bf16 v[18:33], v[12:15], v[8:11], v[18:33]
	ds_read_b64_tr_b16 v[14:15], v194 offset:15424
	ds_read_b64_tr_b16 v[12:13], v194 offset:14400
	v_cvt_pk_bf16_f32 v11, v64, v51
	v_cvt_pk_bf16_f32 v10, v62, v63
	v_cvt_pk_bf16_f32 v9, v60, v61
	v_cvt_pk_bf16_f32 v8, v58, v59
	s_waitcnt lgkmcnt(2)
	s_nop 0
	v_mfma_f32_32x32x16_bf16 v[34:49], v[4:7], v[8:11], v[34:49]
	v_mov_b32_e32 v4, v50
	s_nop 1
	v_permlane32_swap_b32_e32 v50, v4
	v_add_f32_e32 v4, v50, v4
	v_fmac_f32_e32 v4, v169, v2
	s_waitcnt lgkmcnt(0)
	v_mfma_f32_32x32x16_bf16 v[18:33], v[12:15], v[8:11], v[18:33]
	v_mov_b32_e32 v169, v4

; DI float fexp2(float x) { return __builtin_amdgcn_exp2f(x); }
; DI f32x16 mfma32(bf16x8 a, bf16x8 b, f32x16 c) { return __builtin_amdgcn_mfma_f32_32x32x16_bf16(a, b, c, 0, 0, 0); }
; DI f32x16 zero16() { f32x16 z; for (int i = 0; i < 16; ++i) z[i] = 0.f; return z; }
; template <int MASK, bool NEAR, int PASS>
; DI void flash_tile(Flash& st, const bf16x8 (&qf)[4], const char* kbuf, const char* vbuf, int pos0, int qpos, bool on,
;                    const float* lut, float bfar, float* imp_row, float rinv) {
;     ...
;     for (int ks = 0; ks < 4; ++ks) {
;         const int ka = r * 128 + (((2 * ks + h) ^ ((r >> 1) & 7)) << 4);
;         const bf16x8 a0 = *(const bf16x8*)(kbuf + ka);
;         const bf16x8 a1 = *(const bf16x8*)(kbuf + 4096 + ka);
;         s[0] = mfma32(a0, qf[ks], s[0]);
;         s[1] = mfma32(a1, qf[ks], s[1]);
;     }
;     constexpr float c1 = 0.125f * LOG2E;
;     float alpha = 1.f;
;     float rs = 0.f;
;     if (!NEAR) {
;         const float bc = MASK == 2 ? 0.f : bfar;
;         float mref;
;         if (PASS != 2) {
;             float mr = s[0][0];
; #pragma unroll
;             for (int i = 1; i < 16; ++i) mr = fmaxf(mr, s[0][i]);
; #pragma unroll
;             for (int i = 0; i < 16; ++i) mr = fmaxf(mr, s[1][i]);
;             float mx = on ? mr * c1 + bc : -1e30f;
;             mx = fmaxf(mx, __shfl_xor(mx, 32));
;             const float mnew = fmaxf(st.m, mx);
;             alpha = fexp2(st.m - mnew);
;             st.m = mnew;
;             mref = mnew;
;         } else mref = st.m;
;         float bm = on ? bc - mref : -1e30f;
;         if (PASS == 2) bm = on ? bm + __log2f(rinv) : -1e30f;
; #pragma unroll
;         for (int tt = 0; tt < 2; ++tt)
; #pragma unroll
;             for (int i = 0; i < 16; ++i) { const float pv = fexp2(s[tt][i] * c1 + bm); s[tt][i] = pv; rs += pv; }
;     ...
;     if (PASS != 2) {
;         rs += __shfl_xor(rs, 32);
;         st.l = st.l * alpha + rs;
;     }
;     f32x16 ia = zero16();
;     if (PASS != 1) {
;         if (PASS == 0) {
; #pragma unroll
;             for (int i = 0; i < 16; ++i) { st.o0[i] *= alpha; st.o1[i] *= alpha; }
;         }
.LBB0_1375:
	s_ashr_i32 s2, s22, 6
	s_cmpk_gt_i32 s2, 0x7f
	s_cselect_b64 vcc, -1, 0
	s_cmp_lt_i32 s2, 64
	s_cselect_b64 s[0:1], -1, 0
	v_cndmask_b32_e64 v5, v1, v157, s[0:1]
	v_cndmask_b32_e64 v4, v154, v174, s[0:1]
	v_lshrrev_b64 v[4:5], s2, v[4:5]
	v_and_b32_e32 v2, 1, v4
	v_cmp_eq_u32_e64 s[0:1], 1, v2
	s_and_b64 s[0:1], s[8:9], s[0:1]
	s_nop 0
	v_cndmask_b32_e64 v2, 0, 1, s[0:1]
	v_cndmask_b32_e32 v2, v2, v180, vcc
	v_and_b32_e32 v2, 1, v2
	v_cmp_eq_u32_e64 s[0:1], 1, v2
	v_cmp_ne_u32_e32 vcc, 0, v2
	s_cbranch_vccz .LBB0_1363
	ds_read_b128 v[50:53], v190 offset:16384
	ds_read_b128 v[138:141], v190 offset:20480
	ds_read_b128 v[150:153], v191 offset:16384
	ds_read_b128 v[12:15], v191 offset:20480
	ds_read_b128 v[146:149], v192 offset:16384
	ds_read_b128 v[8:11], v192 offset:20480
	ds_read_b128 v[142:145], v193 offset:16384
	ds_read_b128 v[4:7], v193 offset:20480
	s_add_i32 s2, s22, 0xb0
	v_cmp_le_i32_e32 vcc, s2, v226
	s_and_saveexec_b64 s[2:3], vcc
	s_xor_b64 s[2:3], exec, s[2:3]
	s_cbranch_execz .LBB0_1378
	s_waitcnt lgkmcnt(7)
	v_mfma_f32_32x32x16_bf16 v[66:81], v[50:53], v[94:97], 0
	s_waitcnt lgkmcnt(5)
	v_mfma_f32_32x32x16_bf16 v[66:81], v[150:153], v[98:101], v[66:81]
	v_mfma_f32_32x32x16_bf16 v[50:65], v[138:141], v[94:97], 0
	s_waitcnt lgkmcnt(3)
	v_mfma_f32_32x32x16_bf16 v[66:81], v[146:149], v[102:105], v[66:81]
	v_mfma_f32_32x32x16_bf16 v[50:65], v[12:15], v[98:101], v[50:65]
	s_waitcnt lgkmcnt(1)
	v_mfma_f32_32x32x16_bf16 v[66:81], v[142:145], v[106:109], v[66:81]
	v_mfma_f32_32x32x16_bf16 v[50:65], v[8:11], v[102:105], v[50:65]
	s_nop 10
	v_max3_f32 v2, v66, v67, v68
	v_max_f32_e32 v2, v2, v69
	v_max3_f32 v2, v2, v70, v71
	v_max3_f32 v2, v2, v72, v73
	v_max3_f32 v2, v2, v74, v75
	s_waitcnt lgkmcnt(0)
	v_mfma_f32_32x32x16_bf16 v[50:65], v[4:7], v[106:109], v[50:65]
	v_max3_f32 v2, v2, v76, v77
	v_max3_f32 v2, v2, v78, v79
	v_max3_f32 v2, v2, v80, v81
	s_nop 8
	v_max3_f32 v2, v2, v50, v51
	v_max3_f32 v2, v2, v52, v53
	v_max3_f32 v2, v2, v54, v55
	v_max3_f32 v2, v2, v56, v57
	v_max3_f32 v2, v2, v58, v59
	v_max3_f32 v2, v2, v60, v61
	v_max3_f32 v2, v2, v62, v63
	v_max3_f32 v2, v2, v64, v65
	v_fmamk_f32 v2, v2, 0x3e38aa3b, v225
	v_cndmask_b32_e64 v2, v215, v2, s[0:1]
	v_mov_b32_e32 v4, v2
	s_nop 1
	v_permlane32_swap_b32_e32 v2, v4
	v_max3_f32 v16, v181, v2, v4
	v_sub_f32_e32 v4, v16, v181
	v_cmp_lt_f32_e32 vcc, 0x41000000, v4
	v_cndmask_b32_e32 v16, v181, v16, vcc
	s_mov_b64 s[100:101], vcc
	v_sub_f32_e32 v4, v225, v16
	v_cndmask_b32_e64 v17, v215, v4, s[0:1]
	v_fmamk_f32 v4, v66, 0x3e38aa3b, v17
	v_exp_f32_e32 v8, v4
	v_fmamk_f32 v4, v67, 0x3e38aa3b, v17
	v_exp_f32_e32 v12, v4
	v_fmamk_f32 v4, v68, 0x3e38aa3b, v17
	v_exp_f32_e32 v9, v4
	v_fmamk_f32 v4, v69, 0x3e38aa3b, v17
	v_exp_f32_e32 v13, v4
	v_fmamk_f32 v4, v70, 0x3e38aa3b, v17
	v_exp_f32_e32 v10, v4
	v_fmamk_f32 v4, v71, 0x3e38aa3b, v17
	v_exp_f32_e32 v14, v4
	v_fmamk_f32 v4, v72, 0x3e38aa3b, v17
	v_exp_f32_e32 v11, v4
	v_fmamk_f32 v4, v73, 0x3e38aa3b, v17
	v_exp_f32_e32 v15, v4
	v_fmamk_f32 v4, v74, 0x3e38aa3b, v17
	v_exp_f32_e32 v66, v4
	v_fmamk_f32 v4, v75, 0x3e38aa3b, v17
	v_exp_f32_e32 v67, v4
	v_fmamk_f32 v4, v76, 0x3e38aa3b, v17
	v_exp_f32_e32 v68, v4
	v_fmamk_f32 v4, v77, 0x3e38aa3b, v17
	v_exp_f32_e32 v69, v4
	v_fmamk_f32 v4, v78, 0x3e38aa3b, v17
	v_exp_f32_e32 v70, v4
	v_fmamk_f32 v4, v79, 0x3e38aa3b, v17
	v_exp_f32_e32 v71, v4
	v_fmamk_f32 v4, v80, 0x3e38aa3b, v17
	v_exp_f32_e32 v72, v4
	v_add_f32_e32 v4, v12, v8
	v_add_f32_e32 v4, v9, v4
	v_add_f32_e32 v4, v13, v4
	v_add_f32_e32 v4, v10, v4
	v_add_f32_e32 v4, v14, v4
	v_add_f32_e32 v4, v11, v4
	v_add_f32_e32 v4, v15, v4
	v_add_f32_e32 v4, v66, v4
	v_add_f32_e32 v4, v67, v4
	v_fmamk_f32 v5, v81, 0x3e38aa3b, v17
	v_add_f32_e32 v4, v68, v4
	v_add_f32_e32 v4, v69, v4
	v_exp_f32_e32 v73, v5
	v_fmamk_f32 v5, v50, 0x3e38aa3b, v17
	v_add_f32_e32 v4, v70, v4
	v_exp_f32_e32 v50, v5
	v_fmamk_f32 v5, v51, 0x3e38aa3b, v17
	v_add_f32_e32 v4, v71, v4
	v_exp_f32_e32 v51, v5
	v_fmamk_f32 v5, v52, 0x3e38aa3b, v17
	v_add_f32_e32 v4, v72, v4
	v_exp_f32_e32 v52, v5
	v_fmamk_f32 v5, v53, 0x3e38aa3b, v17
	v_add_f32_e32 v4, v73, v4
	v_exp_f32_e32 v53, v5
	v_fmamk_f32 v5, v54, 0x3e38aa3b, v17
	v_add_f32_e32 v4, v50, v4
	v_exp_f32_e32 v54, v5
	v_fmamk_f32 v5, v55, 0x3e38aa3b, v17
	v_add_f32_e32 v4, v51, v4
	v_exp_f32_e32 v55, v5
	v_fmamk_f32 v5, v56, 0x3e38aa3b, v17
	v_add_f32_e32 v4, v52, v4
	v_exp_f32_e32 v56, v5
	v_fmamk_f32 v5, v57, 0x3e38aa3b, v17
	v_add_f32_e32 v4, v53, v4
	v_exp_f32_e32 v57, v5
	v_fmamk_f32 v5, v58, 0x3e38aa3b, v17
	v_add_f32_e32 v4, v54, v4
	v_exp_f32_e32 v58, v5
	v_fmamk_f32 v5, v59, 0x3e38aa3b, v17
	v_add_f32_e32 v4, v55, v4
	v_exp_f32_e32 v59, v5
	v_fmamk_f32 v5, v60, 0x3e38aa3b, v17
	v_add_f32_e32 v4, v56, v4
	v_exp_f32_e32 v60, v5
	v_add_f32_e32 v4, v57, v4
	v_add_f32_e32 v4, v58, v4
	v_add_f32_e32 v4, v59, v4
	v_sub_f32_e32 v2, v181, v16
	v_add_f32_e32 v74, v60, v4
	v_fmamk_f32 v4, v61, 0x3e38aa3b, v17
	v_exp_f32_e32 v2, v2
	v_exp_f32_e32 v61, v4
	ds_read_b64_tr_b16 v[4:5], v194 offset:24576
	ds_read_b64_tr_b16 v[6:7], v194 offset:25600
	v_cvt_pk_bf16_f32 v11, v11, v15
	v_cvt_pk_bf16_f32 v10, v10, v14
	v_cvt_pk_bf16_f32 v9, v9, v13
	v_cvt_pk_bf16_f32 v8, v8, v12
	ds_read_b64_tr_b16 v[14:15], v194 offset:25664
	ds_read_b64_tr_b16 v[12:13], v194 offset:24640
	s_cmp_eq_u64 s[100:101], 0
	s_cbranch_scc1 .Llz_selB
	v_pk_mul_f32 v[48:49], v[48:49], v[2:3] op_sel_hi:[1,0]
	v_pk_mul_f32 v[46:47], v[46:47], v[2:3] op_sel_hi:[1,0]
	v_pk_mul_f32 v[44:45], v[44:45], v[2:3] op_sel_hi:[1,0]
	v_pk_mul_f32 v[42:43], v[42:43], v[2:3] op_sel_hi:[1,0]
	v_pk_mul_f32 v[40:41], v[40:41], v[2:3] op_sel_hi:[1,0]
	v_pk_mul_f32 v[38:39], v[38:39], v[2:3] op_sel_hi:[1,0]
	v_pk_mul_f32 v[36:37], v[36:37], v[2:3] op_sel_hi:[1,0]
	v_pk_mul_f32 v[34:35], v[34:35], v[2:3] op_sel_hi:[1,0]
	v_pk_mul_f32 v[32:33], v[32:33], v[2:3] op_sel_hi:[1,0]
	v_pk_mul_f32 v[30:31], v[30:31], v[2:3] op_sel_hi:[1,0]
	v_pk_mul_f32 v[28:29], v[28:29], v[2:3] op_sel_hi:[1,0]
	v_pk_mul_f32 v[26:27], v[26:27], v[2:3] op_sel_hi:[1,0]
	v_pk_mul_f32 v[24:25], v[24:25], v[2:3] op_sel_hi:[1,0]
	v_pk_mul_f32 v[22:23], v[22:23], v[2:3] op_sel_hi:[1,0]
	v_pk_mul_f32 v[20:21], v[20:21], v[2:3] op_sel_hi:[1,0]
	v_pk_mul_f32 v[18:19], v[18:19], v[2:3] op_sel_hi:[1,0]
; DI f32x16 mfma32(bf16x8 a, bf16x8 b, f32x16 c) { return __builtin_amdgcn_mfma_f32_32x32x16_bf16(a, b, c, 0, 0, 0); }
; DI int opaque(int v) { asm volatile("" : "+v"(v)); return v; }
; template <int MASK, bool NEAR, int PASS>
; DI void flash_tile(Flash& st, const bf16x8 (&qf)[4], const char* kbuf, const char* vbuf, int pos0, int qpos, bool on,
;                    const float* lut, float bfar, float* imp_row, float rinv) {
;     ...
;     if (PASS != 2) {
;         rs += __shfl_xor(rs, 32);
;         st.l = st.l * alpha + rs;
;     }
;     ...
;         const int G = lane >> 4, i16 = lane & 15, q = i16 >> 2, pp = i16 & 3;
;         const char* vb = vbuf + (4 * (G >> 1) + q) * 128 + (16 * (G & 1) + 4 * pp) * 2;
; #pragma unroll
;         for (int tt = 0; tt < 2; ++tt)
; #pragma unroll
;             for (int ss = 0; ss < 2; ++ss) {
;                 f32x4 pa = {s[tt][8 * ss], s[tt][8 * ss + 1], s[tt][8 * ss + 2], s[tt][8 * ss + 3]};
;                 f32x4 pb2 = {s[tt][8 * ss + 4], s[tt][8 * ss + 5], s[tt][8 * ss + 6], s[tt][8 * ss + 7]};
;                 const bf16x8 pfrag = cvt8(pa, pb2);
;                 const char* vk = vb + (32 * tt + 16 * ss) * 128;
;                 if (PASS == 2) {
;                     const int d = opaque((lane & 31) - h) - (8 * tt + 4 * ss);
;                     const unsigned one2 = 0x3F803F80u, oneh = 0x3F800000u;
;                     const uint4 ov = {d == 0 ? one2 : 0u, d == 0 ? one2 : (d == 1 ? oneh : 0u), d == 2 ? one2 : 0u, d == 2 ? one2 : (d == 3 ? oneh : 0u)};
;                     ia = mfma32(__builtin_bit_cast(bf16x8, ov), pfrag, ia);
;                 }
;                 {
;                     const s16x4 lo = tr_read(vk), hi = tr_read(vk + 8 * 128);
;                     const bf16x8 va = __builtin_shufflevector(lo, hi, 0, 1, 2, 3, 4, 5, 6, 7);
;                     st.o0 = mfma32(va, pfrag, st.o0);
;                 }
;                 {
;                     const s16x4 lo = tr_read(vk + 64), hi = tr_read(vk + 8 * 128 + 64);
;                     const bf16x8 va = __builtin_shufflevector(lo, hi, 0, 1, 2, 3, 4, 5, 6, 7);
;                     st.o1 = mfma32(va, pfrag, st.o1);
;                 }
;             }
.Llz_selB:
	s_waitcnt lgkmcnt(2)
	v_mfma_f32_32x32x16_bf16 v[34:49], v[4:7], v[8:11], v[34:49]
	ds_read_b64_tr_b16 v[4:5], v194 offset:26624
	ds_read_b64_tr_b16 v[6:7], v194 offset:27648
	v_fmamk_f32 v64, v64, 0x3e38aa3b, v17
	v_exp_f32_e32 v64, v64
	v_add_f32_e32 v74, v61, v74
	v_mov_b32_e32 v181, v16
	s_waitcnt lgkmcnt(2)
	v_mfma_f32_32x32x16_bf16 v[18:33], v[12:15], v[8:11], v[18:33]
	ds_read_b64_tr_b16 v[14:15], v194 offset:27712
	ds_read_b64_tr_b16 v[12:13], v194 offset:26688
	v_cvt_pk_bf16_f32 v11, v72, v73
	v_cvt_pk_bf16_f32 v10, v70, v71
	v_cvt_pk_bf16_f32 v9, v68, v69
	v_cvt_pk_bf16_f32 v8, v66, v67
	s_waitcnt lgkmcnt(2)
	s_nop 0
	v_mfma_f32_32x32x16_bf16 v[34:49], v[4:7], v[8:11], v[34:49]
	v_fmamk_f32 v4, v62, 0x3e38aa3b, v17
	v_exp_f32_e32 v62, v4
	v_fmamk_f32 v4, v63, 0x3e38aa3b, v17
	v_exp_f32_e32 v63, v4
	ds_read_b64_tr_b16 v[4:5], v194 offset:28672
	ds_read_b64_tr_b16 v[6:7], v194 offset:29696
	v_fmac_f32_e32 v17, 0x3e38aa3b, v65
	v_exp_f32_e32 v17, v17
	s_waitcnt lgkmcnt(2)
	v_mfma_f32_32x32x16_bf16 v[18:33], v[12:15], v[8:11], v[18:33]
	ds_read_b64_tr_b16 v[14:15], v194 offset:29760
	ds_read_b64_tr_b16 v[12:13], v194 offset:28736
	v_cvt_pk_bf16_f32 v11, v56, v57
	v_cvt_pk_bf16_f32 v10, v54, v55
	v_cvt_pk_bf16_f32 v9, v52, v53
	v_cvt_pk_bf16_f32 v8, v50, v51
	s_waitcnt lgkmcnt(2)
	s_nop 0
	v_mfma_f32_32x32x16_bf16 v[34:49], v[4:7], v[8:11], v[34:49]
	v_add_f32_e32 v4, v62, v74
	v_add_f32_e32 v4, v63, v4
	v_add_f32_e32 v50, v64, v4
	ds_read_b64_tr_b16 v[4:5], v194 offset:30720
	ds_read_b64_tr_b16 v[6:7], v194 offset:31744
	v_add_f32_e32 v50, v17, v50
	s_waitcnt lgkmcnt(2)
	v_mfma_f32_32x32x16_bf16 v[18:33], v[12:15], v[8:11], v[18:33]
	ds_read_b64_tr_b16 v[14:15], v194 offset:31808
	ds_read_b64_tr_b16 v[12:13], v194 offset:30784
	v_cvt_pk_bf16_f32 v11, v64, v17
	v_cvt_pk_bf16_f32 v10, v62, v63
	v_cvt_pk_bf16_f32 v9, v60, v61
	v_cvt_pk_bf16_f32 v8, v58, v59
	s_waitcnt lgkmcnt(2)
	s_nop 0
	v_mfma_f32_32x32x16_bf16 v[34:49], v[4:7], v[8:11], v[34:49]
	v_mov_b32_e32 v4, v50
	s_nop 1
	v_permlane32_swap_b32_e32 v50, v4
	v_add_f32_e32 v4, v50, v4
	v_fmac_f32_e32 v4, v169, v2
	s_waitcnt lgkmcnt(0)
	v_mfma_f32_32x32x16_bf16 v[18:33], v[12:15], v[8:11], v[18:33]
	v_mov_b32_e32 v169, v4

;     static DI int kmap(int kt) { return (kt >> 1) + 16 * (kt & 1); }
; template <class AL>
; DI void gemm_mainloop(f32x16 (&acc)[2][2], GemmRegs<AL>& G, bool pre, const AL& al, const u16* __restrict__ Bt, int ldb, int n0, int nk, char* sm,
;                       bool has_next, const AL& aln, int n0n) {
;     ...
;     for (int kt = 0; kt < nk; kt += 2) {
;         compute(buf0);
;         store(RA1, RB1, kt + 1, buf1);
;         if (kt + 3 < nk) { al.load(RA1, AL::kmap(kt + 3)); loadB(RB1, AL::kmap(kt + 3)); }
;         else if (has_next) { aln.load(RA1, AL::kmap(1)); loadBn(RB1, AL::kmap(1)); }
;         __syncthreads();
;         compute(buf1);
;         if (kt + 2 < nk) {
;             store(RA0, RB0, kt + 2, buf0);
;             if (kt + 4 < nk) { al.load(RA0, AL::kmap(kt + 4)); loadB(RB0, AL::kmap(kt + 4)); }
;             else if (has_next) { aln.load(RA0, AL::kmap(0)); loadBn(RB0, AL::kmap(0)); }
;         }
;         __syncthreads();
;     }
; DI void phase5(const Params& p, char* sm) {
;     ...
;     for (int s2 = blockIdx.x >> 3; s2 < 128; s2 += nb) {
;         const int s2n = s2 + nb; const bool hn = s2n < 128;
;         gemm2_tile<false>(p, G, pre, s2, x, hn, s2n, x, sm);
;         pre = hn;
;     }
.Lg5_loop:
	s_setprio 1
	v_add_u32_e32 v228, v222, v223
	v_add_u32_e32 v229, v224, v223
	v_add_u32_e32 v230, v222, v225
	v_add_u32_e32 v231, v224, v225
	ds_read_b128 v[204:207], v228
	ds_read_b128 v[208:211], v228 offset:4096
	ds_read_b128 v[212:215], v229 offset:16384
	ds_read_b128 v[216:219], v229 offset:20480
	ds_read_b128 v[234:237], v230
	ds_read_b128 v[238:241], v230 offset:4096
	ds_read_b128 v[242:245], v231 offset:16384
	ds_read_b128 v[246:249], v231 offset:20480
	s_mov_b32 m0, s70
	s_nop 0
	global_load_lds_dwordx4 v190, s[26:27]
	global_load_lds_dwordx4 v191, s[26:27] offset:1024
	global_load_lds_dwordx4 v192, s[26:27] offset:2048
	global_load_lds_dwordx4 v193, s[26:27] offset:3072
	s_add_u32 s26, s26, 0x80
	s_addc_u32 s27, s27, 0
	s_waitcnt lgkmcnt(5)
	v_mfma_f32_32x32x16_bf16 v[50:65], v[204:207], v[212:215], v[50:65]
	v_add_u32_e32 v232, v222, v226
	v_add_u32_e32 v233, v224, v226
	s_waitcnt lgkmcnt(4)
	v_mfma_f32_32x32x16_bf16 v[34:49], v[204:207], v[216:219], v[34:49]
	v_mfma_f32_32x32x16_bf16 v[18:33], v[208:211], v[212:215], v[18:33]
	v_mfma_f32_32x32x16_bf16 v[2:17], v[208:211], v[216:219], v[2:17]
	ds_read_b128 v[204:207], v232
	ds_read_b128 v[208:211], v232 offset:4096
	ds_read_b128 v[212:215], v233 offset:16384
	ds_read_b128 v[216:219], v233 offset:20480
	s_mov_b32 m0, s71
	s_nop 0
	global_load_lds_dwordx4 v190, s[28:29]
	global_load_lds_dwordx4 v191, s[28:29] offset:1024
	global_load_lds_dwordx4 v192, s[28:29] offset:2048
	global_load_lds_dwordx4 v193, s[28:29] offset:3072
	s_add_u32 s28, s28, 0x80
	s_addc_u32 s29, s29, 0
	s_waitcnt lgkmcnt(5)
	v_mfma_f32_32x32x16_bf16 v[50:65], v[234:237], v[242:245], v[50:65]
	s_waitcnt lgkmcnt(4)
	v_mfma_f32_32x32x16_bf16 v[34:49], v[234:237], v[246:249], v[34:49]
	v_add_u32_e32 v234, v222, v227
	v_add_u32_e32 v235, v224, v227
	v_mfma_f32_32x32x16_bf16 v[18:33], v[238:241], v[242:245], v[18:33]
	v_mfma_f32_32x32x16_bf16 v[2:17], v[238:241], v[246:249], v[2:17]
	ds_read_b128 v[236:239], v234
	ds_read_b128 v[240:243], v234 offset:4096
	ds_read_b128 v[244:247], v235 offset:16384
	ds_read_b128 v[248:251], v235 offset:20480
	s_waitcnt lgkmcnt(5)
	v_mfma_f32_32x32x16_bf16 v[50:65], v[204:207], v[212:215], v[50:65]
	s_waitcnt lgkmcnt(4)
	v_mfma_f32_32x32x16_bf16 v[34:49], v[204:207], v[216:219], v[34:49]
	v_mfma_f32_32x32x16_bf16 v[18:33], v[208:211], v[212:215], v[18:33]
	v_mfma_f32_32x32x16_bf16 v[2:17], v[208:211], v[216:219], v[2:17]
	s_waitcnt lgkmcnt(1)
	v_mfma_f32_32x32x16_bf16 v[50:65], v[236:239], v[244:247], v[50:65]
	s_waitcnt lgkmcnt(0)
	v_mfma_f32_32x32x16_bf16 v[34:49], v[236:239], v[248:251], v[34:49]
	v_mfma_f32_32x32x16_bf16 v[18:33], v[240:243], v[244:247], v[18:33]
	v_mfma_f32_32x32x16_bf16 v[2:17], v[240:243], v[248:251], v[2:17]
	s_waitcnt vmcnt(0)
	s_barrier
	s_mov_b32 s34, 1
	s_cmp_lt_u32 s32, 14
	s_cbranch_scc1 .Lg5_bgo
	s_mov_b32 s34, 0
	s_and_b64 vcc, exec, s[24:25]
	s_cbranch_vccnz .Lg5_bgo
	s_mov_b32 s34, 1
	s_lshl_b32 s73, s93, 18
	s_add_u32 s26, s42, s73
	s_addc_u32 s27, s43, 0
	s_lshl_b32 s73, s45, 11
	s_add_u32 s28, s38, s73
	s_addc_u32 s29, s39, 0

;     static DI int kmap(int kt) { return (kt >> 1) + 16 * (kt & 1); }
; template <class AL>
; DI void gemm_mainloop(f32x16 (&acc)[2][2], GemmRegs<AL>& G, bool pre, const AL& al, const u16* __restrict__ Bt, int ldb, int n0, int nk, char* sm,
;                       bool has_next, const AL& aln, int n0n) {
;     ...
;     for (int kt = 0; kt < nk; kt += 2) {
;         compute(buf0);
;         store(RA1, RB1, kt + 1, buf1);
;         if (kt + 3 < nk) { al.load(RA1, AL::kmap(kt + 3)); loadB(RB1, AL::kmap(kt + 3)); }
;         else if (has_next) { aln.load(RA1, AL::kmap(1)); loadBn(RB1, AL::kmap(1)); }
;         __syncthreads();
;         compute(buf1);
;         if (kt + 2 < nk) {
;             store(RA0, RB0, kt + 2, buf0);
;             if (kt + 4 < nk) { al.load(RA0, AL::kmap(kt + 4)); loadB(RB0, AL::kmap(kt + 4)); }
;             else if (has_next) { aln.load(RA0, AL::kmap(0)); loadBn(RB0, AL::kmap(0)); }
;         }
;         __syncthreads();
;     }
.Lg5_skipB:
	s_waitcnt lgkmcnt(5)
	v_mfma_f32_32x32x16_bf16 v[50:65], v[236:239], v[244:247], v[50:65]
	s_waitcnt lgkmcnt(4)
	v_mfma_f32_32x32x16_bf16 v[34:49], v[236:239], v[228:231], v[34:49]
	v_mfma_f32_32x32x16_bf16 v[18:33], v[240:243], v[244:247], v[18:33]
	v_mfma_f32_32x32x16_bf16 v[2:17], v[240:243], v[228:231], v[2:17]
	ds_read_b128 v[228:231], v234 offset:32768
	ds_read_b128 v[236:239], v234 offset:36864
	ds_read_b128 v[240:243], v235 offset:49152
	ds_read_b128 v[232:235], v235 offset:53248
	s_waitcnt lgkmcnt(5)
	v_mfma_f32_32x32x16_bf16 v[50:65], v[204:207], v[212:215], v[50:65]
	s_waitcnt lgkmcnt(4)
	v_mfma_f32_32x32x16_bf16 v[34:49], v[204:207], v[216:219], v[34:49]
	v_mfma_f32_32x32x16_bf16 v[18:33], v[208:211], v[212:215], v[18:33]
	v_mfma_f32_32x32x16_bf16 v[2:17], v[208:211], v[216:219], v[2:17]
	s_waitcnt lgkmcnt(1)
	v_mfma_f32_32x32x16_bf16 v[50:65], v[228:231], v[240:243], v[50:65]
	s_waitcnt lgkmcnt(0)
	v_mfma_f32_32x32x16_bf16 v[34:49], v[228:231], v[232:235], v[34:49]
	v_mfma_f32_32x32x16_bf16 v[18:33], v[236:239], v[240:243], v[18:33]
	v_mfma_f32_32x32x16_bf16 v[2:17], v[236:239], v[232:235], v[2:17]
	s_waitcnt vmcnt(0)
	s_barrier
	s_add_i32 s32, s32, 2
	s_cmp_lt_u32 s32, 16
	s_cbranch_scc1 .Lg5_loop
	s_setprio 0
